# group-1 weights other than WIN also moved into idle-CU windows (WGLU in S5Y phase, WBR in GLU phase, WOUT at G2 exit); WF1 chunks rebalanced
# speedup vs baseline: 1.0119x; 1.0119x over previous
; __device__ __forceinline__ int opaque_tid() { int t = threadIdx.x; asm volatile("" : "+v"(t)); return t; }
; __global__ void __launch_bounds__(512, 2) mega_fwd(Params P) {
;     ...
;             const int tid = opaque_tid(), lane = tid & 63, wave = __builtin_amdgcn_readfirstlane(tid >> 6); const int gw = c * 8 + wave, NGW = (G + z) * 8;
;             const float* win = PIN(I_WIN) + (size_t)l * D * 12288; const float* wbr = PIN(I_WBR) + (size_t)l * 3 * 1024 * D; const float* wout = PIN(I_WOUT) + (size_t)l * D * D;
;             const float* wglu = PIN(I_S5WG) + (size_t)l * 1024 * 1024;
;             const int n_in = 32 * 48, n_br = 16 * 8, n_out = 32 * 8, n_glu = 16 * 4; const int tot = n_in + 3 * n_br + n_out + n_glu;
;             { const int tot4 = tot * 4; const int s0 = (int)((unsigned)(gw * tot4) / (unsigned)NGW), s1 = (int)((unsigned)((gw + 1) * tot4) / (unsigned)NGW);
;             for (int ss = s0; ss < s1; ++ss) {
;                 int r = ss >> 2; const int sub = ss & 3;
;                 if (r < n_in) { transpose_item<0>(win, D, 12288, WIN, r, sub, lane); continue; } r -= n_in;
;                 if (r < 3 * n_br) { const int i = r / n_br; transpose_item<0>(wbr + (size_t)i * 1024 * D, 1024, D, WBR + (size_t)i * D * 1024, r - i * n_br, sub, lane); continue; } r -= 3 * n_br;
;                 if (r < n_out) { transpose_item<0>(wout, D, D, WOUT, r, sub, lane); continue; } r -= n_out;
;                 transpose_item<0>(wglu, 1024, 1024, WGLU, r, sub, lane);
;             } }
.LBB0_48:
	v_writelane_b32 v254, s24, 57
	s_nop 1
	v_writelane_b32 v254, s25, 58
	s_or_b64 exec, exec, s[0:1]
	s_mov_b32 s100, s64
	s_mov_b32 s101, s51
	s_mov_b32 s4, 0x1800
	v_writelane_b32 v255, s4, 50
	s_nop 1
	s_mov_b32 s4, 0x0
	v_writelane_b32 v255, s4, 51
	s_nop 1
	s_mov_b32 s4, 0x0
	v_writelane_b32 v255, s4, 54
	s_nop 1
.Lw1_entry:
	v_mov_b32_e32 v0, v162
	v_mov_b32_e32 v2, v163
	v_mov_b32_e32 v46, v208
	v_readfirstlane_b32 s34, v0
	v_mov_b32_e32 v0, v1
	v_readlane_b32 s4, v254, 30
	v_readfirstlane_b32 s0, v0
	s_add_i32 s1, s0, s100
	s_lshl_b32 s14, s1, 3
	v_cvt_f32_u32_e32 v0, s14
	v_readfirstlane_b32 s1, v46
	s_lshr_b32 s1, s1, 6
	s_add_i32 s15, s1, s101
	v_rcp_iflag_f32_e32 v0, v0
	s_ashr_i32 s1, s0, 31
	s_lshl_b64 s[0:1], s[0:1], 3
	v_readlane_b32 s5, v254, 31
	v_mul_f32_e32 v0, 0x4f7ffffe, v0
	v_cvt_u32_f32_e32 v0, v0
	s_add_u32 s4, s4, s0
	s_addc_u32 s5, s5, s1
	v_readlane_b32 s16, v255, 50
	s_nop 1
	s_mul_i32 s0, s15, s16
	s_sub_i32 s1, 0, s14
	v_readfirstlane_b32 s15, v0
	s_mul_i32 s1, s1, s15
	s_mul_hi_u32 s1, s15, s1
	s_add_i32 s15, s15, s1
	s_mul_hi_u32 s1, s0, s15
	s_mul_i32 s16, s1, s14
	s_sub_i32 s16, s0, s16
	s_add_i32 s17, s1, 1
	s_sub_i32 s18, s16, s14
	s_cmp_ge_u32 s16, s14
	s_cselect_b32 s1, s17, s1
	s_cselect_b32 s16, s18, s16
	s_add_i32 s17, s1, 1
	s_cmp_ge_u32 s16, s14
	s_cselect_b32 s24, s17, s1
	v_readlane_b32 s1, v255, 50
	s_nop 1
	s_add_i32 s0, s0, s1
	s_mul_hi_u32 s1, s0, s15
	s_mul_i32 s15, s1, s14
	s_sub_i32 s0, s0, s15
	s_add_i32 s15, s1, 1
	s_sub_i32 s16, s0, s14
	s_cmp_ge_u32 s0, s14
	s_cselect_b32 s1, s15, s1
	s_cselect_b32 s0, s16, s0
	s_add_i32 s15, s1, 1
	s_cmp_ge_u32 s0, s14
	s_cselect_b32 s25, s15, s1
	v_readlane_b32 s1, v255, 51
	s_nop 1
	s_add_i32 s24, s24, s1
	s_add_i32 s25, s25, s1
	s_cmp_lt_i32 s24, s25
	v_readfirstlane_b32 s35, v2
	s_cbranch_scc0 .LBB0_63
	v_readlane_b32 s0, v254, 53
	v_readlane_b32 s1, v254, 54
	s_mul_i32 s16, s0, 0x6000000
	s_mul_i32 s28, s0, 0x1800000
	s_lshl_b64 s[14:15], s[0:1], 24
	s_lshl_b64 s[30:31], s[0:1], 22
	s_load_dwordx2 s[0:1], s[4:5], 0x20
	v_lshlrev_b32_e32 v0, 2, v46
	v_and_b32_e32 v47, 0xfc, v0
	s_waitcnt lgkmcnt(0)
	s_add_u32 s0, s0, s16
	s_load_dwordx4 s[16:19], s[4:5], 0xc8
	s_addc_u32 s1, s1, 0
	s_waitcnt lgkmcnt(0)
	s_add_u32 s28, s16, s28
	s_addc_u32 s29, s17, 0
	s_load_dwordx2 s[16:17], s[4:5], 0xb0
	s_add_u32 s14, s18, s14
	s_addc_u32 s15, s19, s15
	s_waitcnt lgkmcnt(0)
	s_add_u32 s16, s16, s30
	s_addc_u32 s17, s17, s31
	s_add_u32 s30, s34, 0x4400000
	s_addc_u32 s31, s35, 0
	s_add_u32 s40, s34, 0x3c00000
	s_addc_u32 s41, s35, 0
	s_add_u32 s42, s34, 0x3000000
	s_addc_u32 s43, s35, 0
	s_branch .LBB0_51

; __global__ void __launch_bounds__(512, 2) mega_fwd(Params P) {
;     ...
;             for (int ss = s0; ss < s1; ++ss) {
;                 int r = ss >> 2; const int sub = ss & 3;
;                 if (r < n_in) { transpose_item<0>(win, D, 12288, WIN, r, sub, lane); continue; } r -= n_in;
;                 if (r < 3 * n_br) { const int i = r / n_br; transpose_item<0>(wbr + (size_t)i * 1024 * D, 1024, D, WBR + (size_t)i * D * 1024, r - i * n_br, sub, lane); continue; } r -= 3 * n_br;
;                 if (r < n_out) { transpose_item<0>(wout, D, D, WOUT, r, sub, lane); continue; } r -= n_out;
;                 transpose_item<0>(wglu, 1024, 1024, WGLU, r, sub, lane);
;             } }
.LBB0_63:
	v_readlane_b32 s0, v255, 54
	s_nop 3
	s_cmp_eq_u32 s0, 0
	s_cbranch_scc1 .Lw1_norm
	s_cmp_eq_u32 s0, 1
	s_cbranch_scc1 .Ltr_w1_ret_s5y
	s_cmp_eq_u32 s0, 2
	s_cbranch_scc1 .Ltr_w1_ret_glu
	s_branch .Ltr_w1_ret_g2

; __device__ __forceinline__ void attn_phase(LAS unsigned char* lds, bf16_t* p5, const bf16_t* vt, const float* relb, const float* dalam, const float* subln, float lam_init, int ocol) {
;     ...
;     for (int r = 0;; ++r) {
;         const int idx = (r & 1) ? r * G + (G - 1 - c) : r * G + c;
;         if (r * G >= 33 * 32) break;
;         if (idx >= 33 * 32) continue;
; __global__ void __launch_bounds__(512, 2) mega_fwd(Params P) {
;     ...
;             { const int tot4 = tot * 4; const int s0 = (int)((unsigned)(gw * tot4) / (unsigned)NGW), s1 = (int)((unsigned)((gw + 1) * tot4) / (unsigned)NGW);
;             for (int ss = s0; ss < s1; ++ss) {
;                 int r = ss >> 2; const int sub = ss & 3;
;                 if (r < n_in) { transpose_item<0>(win, D, 12288, WIN, r, sub, lane); continue; } r -= n_in;
;                 if (r < 3 * n_br) { const int i = r / n_br; transpose_item<0>(wbr + (size_t)i * 1024 * D, 1024, D, WBR + (size_t)i * D * 1024, r - i * n_br, sub, lane); continue; } r -= 3 * n_br;
;                 if (r < n_out) { transpose_item<0>(wout, D, D, WOUT, r, sub, lane); continue; } r -= n_out;
;                 transpose_item<0>(wglu, 1024, 1024, WGLU, r, sub, lane);
;             } }
.Ltr_w1_entry:
	s_branch .Lw1_entry
.Ltr_w1_ret_s5y:
	s_branch .Lw1_ret_s5y
.Ltr_w1_ret_glu:
	s_branch .Lw1_ret_glu
.Ltr_w1_ret_g2:
	s_branch .Lw1_ret_g2
.LBB0_642:
	s_andn2_b64 vcc, exec, s[24:25]
	s_cbranch_vccz .LBB0_794

; __device__ __forceinline__ void lru_scan2(bf16_t* p5, const bf16_t* bbuf, const float* agg) {
;     const int gt = blockIdx.x * 512 + opaque_tid(), NGT = gridDim.x * 512;
;     for (int it = gt; it < NB * NCH64 * 512; it += NGT) {
;         const int cp = it & 511, bc = it >> 9; const int b = bc / NCH64, c = bc - b * NCH64; const size_t m0 = (size_t)b * TP + c * 64;
;         float h0 = 0.f, h1 = 0.f;
;         for (int cc0 = 0; cc0 < c; cc0 += 8) {
;             f32x4 a[8];
; #pragma unroll
;             for (int k = 0; k < 8; ++k) a[k] = (cc0 + k < c) ? *(const f32x4*)(agg + ((size_t)(b * NCH64 + cc0 + k) * 512 + cp) * 4) : (f32x4){0.f, 0.f, 0.f, 0.f};
; #pragma unroll
;             for (int k = 0; k < 8; ++k) { h0 = __expf(a[k].x) * h0 + a[k].y; h1 = __expf(a[k].z) * h1 + a[k].w; }
;         }
;         for (int t0 = 0; t0 < 64; t0 += 8) {
;             unsigned lw[8], bw[8], gw[8];
; #pragma unroll
;             for (int k = 0; k < 8; ++k) { lw[k] = *(const unsigned*)(p5 + (m0 + t0 + k) * LDP + C_AX + 2 * cp); bw[k] = *(const unsigned*)(bbuf + (m0 + t0 + k) * 1024 + 2 * cp);
;                 gw[k] = *(const unsigned*)(p5 + (m0 + t0 + k) * LDP + C_AG + 2 * cp); }
; #pragma unroll
;             for (int k = 0; k < 8; ++k) { h0 = __expf(bf_lo(lw[k])) * h0 + bf_lo(bw[k]); h1 = __expf(bf_hi(lw[k])) * h1 + bf_hi(bw[k]);
;                 gw[k] = cvt_pk_bf16(h0 * gelu_tanh(bf_lo(gw[k])), h1 * gelu_tanh(bf_hi(gw[k]))); }
; #pragma unroll
;             for (int k = 0; k < 8; ++k) *(unsigned*)(p5 + (m0 + t0 + k) * LDP + C_AG + 2 * cp) = gw[k];
;         }
;     }
; }
; __global__ void __launch_bounds__(512, 2) mega_fwd(Params P) {
;     ...
;             { const int tot4 = tot * 4; const int s0 = (int)((unsigned)(gw * tot4) / (unsigned)NGW), s1 = (int)((unsigned)((gw + 1) * tot4) / (unsigned)NGW);
;             for (int ss = s0; ss < s1; ++ss) {
;                 int r = ss >> 2; const int sub = ss & 3;
;                 if (r < n_in) { transpose_item<0>(win, D, 12288, WIN, r, sub, lane); continue; } r -= n_in;
;                 if (r < 3 * n_br) { const int i = r / n_br; transpose_item<0>(wbr + (size_t)i * 1024 * D, 1024, D, WBR + (size_t)i * D * 1024, r - i * n_br, sub, lane); continue; } r -= 3 * n_br;
;                 if (r < n_out) { transpose_item<0>(wout, D, D, WOUT, r, sub, lane); continue; } r -= n_out;
.Lscan2_done:
	s_or_b64 exec, exec, s[4:5]
	s_cmp_eq_u32 s101, 0xfc00
	s_cbranch_scc1 .Lscan2_ret
	s_mov_b64 exec, -1
	v_writelane_b32 v255, s0, 8
	s_nop 1
	v_writelane_b32 v255, s1, 9
	s_nop 1
	v_writelane_b32 v255, s4, 10
	s_nop 1
	v_writelane_b32 v255, s5, 11
	s_nop 1
	v_writelane_b32 v255, s14, 12
	s_nop 1
	v_writelane_b32 v255, s15, 13
	s_nop 1
	v_writelane_b32 v255, s16, 14
	s_nop 1
	v_writelane_b32 v255, s17, 15
	s_nop 1
	v_writelane_b32 v255, s18, 16
	s_nop 1
	v_writelane_b32 v255, s19, 17
	s_nop 1
	v_writelane_b32 v255, s24, 18
	s_nop 1
	v_writelane_b32 v255, s25, 19
	s_nop 1
	v_writelane_b32 v255, s28, 20
	s_nop 1
	v_writelane_b32 v255, s29, 21
	s_nop 1
	v_writelane_b32 v255, s30, 22
	s_nop 1
	v_writelane_b32 v255, s31, 23
	s_nop 1
	v_writelane_b32 v255, s34, 24
	s_nop 1
	v_writelane_b32 v255, s35, 25
	s_nop 1
	v_writelane_b32 v255, s40, 26
	s_nop 1
	v_writelane_b32 v255, s41, 27
	s_nop 1
	v_writelane_b32 v255, s42, 28
	s_nop 1
	v_writelane_b32 v255, s43, 29
	s_nop 1
	v_writelane_b32 v255, s44, 30
	s_nop 1
	v_writelane_b32 v255, s45, 31
	s_nop 1
	v_writelane_b32 v255, s46, 32
	s_nop 1
	v_writelane_b32 v255, s47, 33
	s_nop 1
	v_writelane_b32 v255, s48, 34
	s_nop 1
	v_writelane_b32 v255, s49, 35
	s_nop 1
	v_writelane_b32 v255, s50, 36
	s_nop 1
	v_writelane_b32 v255, s53, 37
	s_nop 1
	v_writelane_b32 v255, s54, 38
	s_nop 1
	v_writelane_b32 v255, s55, 39
	s_nop 1
	v_writelane_b32 v255, s56, 40
	s_nop 1
	v_writelane_b32 v255, s57, 41
	s_nop 1
	v_writelane_b32 v255, s68, 42
	s_nop 1
	v_writelane_b32 v255, s73, 43
	s_nop 1
	s_movk_i32 s73, 0x2000
	s_movk_i32 s50, 0x6000
	s_mov_b32 s53, 0x8000
	s_mov_b32 s54, 0xa000
	s_mov_b32 s55, 0xc000
	s_mov_b32 s56, 0xe000
	s_mov_b32 s57, 0x16000
	s_movk_i32 s100, 0x80
	s_sub_u32 s101, s2, 0x80
	s_lshl_b32 s101, s101, 3
	s_mov_b32 s4, 0x100
	v_writelane_b32 v255, s4, 50
	s_nop 1
	s_mov_b32 s4, 0x2200
	v_writelane_b32 v255, s4, 51
	s_nop 1
	s_mov_b32 s4, 0x1
	v_writelane_b32 v255, s4, 54
	s_nop 1
	s_branch .Ltr_w1_entry
.Lw1_ret_s5y:
	s_mov_b64 exec, -1
	s_waitcnt vmcnt(0) lgkmcnt(0)
	v_readlane_b32 s0, v255, 8
	v_readlane_b32 s1, v255, 9
	v_readlane_b32 s4, v255, 10
	v_readlane_b32 s5, v255, 11
	v_readlane_b32 s14, v255, 12
	v_readlane_b32 s15, v255, 13
	v_readlane_b32 s16, v255, 14
	v_readlane_b32 s17, v255, 15
	v_readlane_b32 s18, v255, 16
	v_readlane_b32 s19, v255, 17
	v_readlane_b32 s24, v255, 18
	v_readlane_b32 s25, v255, 19
	v_readlane_b32 s28, v255, 20
	v_readlane_b32 s29, v255, 21
	v_readlane_b32 s30, v255, 22
	v_readlane_b32 s31, v255, 23
	v_readlane_b32 s34, v255, 24
	v_readlane_b32 s35, v255, 25
	v_readlane_b32 s40, v255, 26
	v_readlane_b32 s41, v255, 27
	v_readlane_b32 s42, v255, 28
	v_readlane_b32 s43, v255, 29
	v_readlane_b32 s44, v255, 30
	v_readlane_b32 s45, v255, 31
	v_readlane_b32 s46, v255, 32
	v_readlane_b32 s47, v255, 33
	v_readlane_b32 s48, v255, 34
	v_readlane_b32 s49, v255, 35
	v_readlane_b32 s50, v255, 36
	v_readlane_b32 s53, v255, 37
	v_readlane_b32 s54, v255, 38
	v_readlane_b32 s55, v255, 39
	v_readlane_b32 s56, v255, 40
	v_readlane_b32 s57, v255, 41
	v_readlane_b32 s68, v255, 42
	v_readlane_b32 s73, v255, 43
	s_nop 4
	s_branch .Lscan2_skip

; #define PH(b) if ((PHM >> (b)) & 1)
; #define PHASE_BEGIN unsigned char* ws = opaque_ptr(P.ws); const int z = opaque_zero(); (void)ws; (void)z;
; #define GSYNC() xcd_barrier(xbar)
; __global__ void __launch_bounds__(512, 2) mega_fwd(Params P) {
;     ...
;         PH(7) { PHASE_BEGIN
;           lru_scan2(P5, XC, AGG); }
;         GSYNC();
;         PH(9) { PHASE_BEGIN
;           pg8::DenseOrder S{P5 + C_V, WGLU, LDP, 1024, MP / 256, 4, G, c, 16}; pg8::EpiGlu E{P5, PIN(I_S5BG) + (size_t)l * 1024};
;           pg8::gemm_phase(lds, LDP, 1024, S, E); }
.LBB0_1020:
	s_or_b64 exec, exec, s[0:1]
	v_mov_b32_e32 v0, v163
	s_waitcnt lgkmcnt(0)
	v_mov_b32_e32 v2, v162
	s_barrier
	v_readlane_b32 s14, v253, 28
	v_readfirstlane_b32 s5, v0
	v_mov_b32_e32 v0, v1
	v_mov_b32_e32 v18, v208
	v_readlane_b32 s15, v253, 29
	v_readfirstlane_b32 s4, v2
	s_andn2_b64 vcc, exec, s[14:15]
	v_readfirstlane_b32 s0, v0
	v_readfirstlane_b32 s16, v18
	s_cbranch_vccnz .LBB0_1040
	s_cmpk_lt_u32 s2, 0x82
	s_cbranch_scc1 .Lglu_go
	v_writelane_b32 v255, s29, 25
	s_nop 1
	v_writelane_b32 v255, s30, 26
	s_nop 1
	v_writelane_b32 v255, s31, 27
	s_nop 1
	v_writelane_b32 v255, s34, 28
	s_nop 1
	v_writelane_b32 v255, s35, 29
	s_nop 1
	v_writelane_b32 v255, s40, 30
	s_nop 1
	v_writelane_b32 v255, s41, 31
	s_nop 1
	v_writelane_b32 v255, s43, 32
	s_nop 1
	v_writelane_b32 v255, s44, 33
	s_nop 1
	v_writelane_b32 v255, s45, 34
	s_nop 1
	v_writelane_b32 v255, s46, 35
	s_nop 1
	v_writelane_b32 v255, s47, 36
	s_nop 1
	v_writelane_b32 v255, s48, 37
	s_nop 1
	v_writelane_b32 v255, s49, 38
	s_nop 1
	v_writelane_b32 v255, s53, 39
	s_nop 1
	v_writelane_b32 v255, s54, 40
	s_nop 1
	v_writelane_b32 v255, s55, 41
	s_nop 1
	v_writelane_b32 v255, s56, 42
	s_nop 1
	v_writelane_b32 v255, s57, 43
	s_nop 1
	v_writelane_b32 v255, s68, 44
	s_nop 1
	v_writelane_b32 v255, s73, 45
	s_nop 1
	v_writelane_b32 v255, s0, 8
	s_nop 1
	v_writelane_b32 v255, s1, 9
	s_nop 1
	v_writelane_b32 v255, s4, 10
	s_nop 1
	v_writelane_b32 v255, s5, 11
	s_nop 1
	v_writelane_b32 v255, s14, 12
	s_nop 1
	v_writelane_b32 v255, s15, 13
	s_nop 1
	v_writelane_b32 v255, s16, 14
	s_nop 1
	v_writelane_b32 v255, s17, 15
	s_nop 1
	v_writelane_b32 v255, s18, 16
	s_nop 1
	v_writelane_b32 v255, s19, 17
	s_nop 1
	v_writelane_b32 v255, s24, 18
	s_nop 1
	v_writelane_b32 v255, s25, 19
	s_nop 1
	v_writelane_b32 v255, s28, 20
	s_nop 1
	v_writelane_b32 v255, s32, 21
	s_nop 1
	v_writelane_b32 v255, s42, 22
	s_nop 1
	v_writelane_b32 v255, s50, 23
	s_nop 1
	v_writelane_b32 v255, s51, 24
	s_nop 1
	s_sub_u32 s100, s2, 0x82
	s_lshl_b32 s100, s100, 9
	s_add_u32 s100, s100, 0x10000
	s_mov_b32 s101, 0xfc00
	s_mov_b32 s4, 0x20800
	v_writelane_b32 v255, s4, 50
	s_nop 1
	s_branch .Lscan2_entry
.Lscan2_ret:
	s_mov_b64 exec, -1
	s_waitcnt vmcnt(0) lgkmcnt(0)
	s_movk_i32 s73, 0x2000
	s_movk_i32 s50, 0x6000
	s_mov_b32 s53, 0x8000
	s_mov_b32 s54, 0xa000
	s_mov_b32 s55, 0xc000
	s_mov_b32 s56, 0xe000
	s_mov_b32 s57, 0x16000
	s_movk_i32 s100, 0x7e
	s_sub_u32 s101, s2, 0x82
	s_lshl_b32 s101, s101, 3
	s_mov_b32 s4, 0x600
	v_writelane_b32 v255, s4, 50
	s_nop 1
	s_mov_b32 s4, 0x1800
	v_writelane_b32 v255, s4, 51
	s_nop 1
	s_mov_b32 s4, 0x2
	v_writelane_b32 v255, s4, 54
	s_nop 1
	s_branch .Ltr_w1_entry

; #define PH(b) if ((PHM >> (b)) & 1)
; #define PHASE_BEGIN unsigned char* ws = opaque_ptr(P.ws); const int z = opaque_zero(); (void)ws; (void)z;
; __global__ void __launch_bounds__(512, 2) mega_fwd(Params P) {
;     ...
;         PH(9) { PHASE_BEGIN
;           pg8::DenseOrder S{P5 + C_V, WGLU, LDP, 1024, MP / 256, 4, G, c, 16}; pg8::EpiGlu E{P5, PIN(I_S5BG) + (size_t)l * 1024};
;           pg8::gemm_phase(lds, LDP, 1024, S, E); }
.Lw2_ret_glu:
	s_mov_b64 exec, -1
	s_waitcnt vmcnt(0) lgkmcnt(0)
	v_readlane_b32 s29, v255, 25
	v_readlane_b32 s30, v255, 26
	v_readlane_b32 s31, v255, 27
	v_readlane_b32 s34, v255, 28
	v_readlane_b32 s35, v255, 29
	v_readlane_b32 s40, v255, 30
	v_readlane_b32 s41, v255, 31
	v_readlane_b32 s43, v255, 32
	v_readlane_b32 s44, v255, 33
	v_readlane_b32 s45, v255, 34
	v_readlane_b32 s46, v255, 35
	v_readlane_b32 s47, v255, 36
	v_readlane_b32 s48, v255, 37
	v_readlane_b32 s49, v255, 38
	v_readlane_b32 s53, v255, 39
	v_readlane_b32 s54, v255, 40
	v_readlane_b32 s55, v255, 41
	v_readlane_b32 s56, v255, 42
	v_readlane_b32 s57, v255, 43
	v_readlane_b32 s68, v255, 44
	v_readlane_b32 s73, v255, 45
	s_nop 4
	v_readlane_b32 s0, v255, 8
	v_readlane_b32 s1, v255, 9
	v_readlane_b32 s4, v255, 10
	v_readlane_b32 s5, v255, 11
	v_readlane_b32 s14, v255, 12
	v_readlane_b32 s15, v255, 13
	v_readlane_b32 s16, v255, 14
	v_readlane_b32 s17, v255, 15
	v_readlane_b32 s18, v255, 16
	v_readlane_b32 s19, v255, 17
	v_readlane_b32 s24, v255, 18
	v_readlane_b32 s25, v255, 19
	v_readlane_b32 s28, v255, 20
	v_readlane_b32 s32, v255, 21
	v_readlane_b32 s42, v255, 22
	v_readlane_b32 s50, v255, 23
	v_readlane_b32 s51, v255, 24
	s_nop 4
	s_branch .LBB0_1040

; #define PG8_WAIT_V(n) asm volatile("s_waitcnt vmcnt(" #n ")" ::: "memory")
; #define PG8_BAR __builtin_amdgcn_s_barrier()
; #define PH(b) if ((PHM >> (b)) & 1)
; #define PHASE_BEGIN unsigned char* ws = opaque_ptr(P.ws); const int z = opaque_zero(); (void)ws; (void)z;
; #define GSYNC() xcd_barrier(xbar)
; template <class Epi, class Sched>
; __device__ __forceinline__ void gemm_phase(LAS unsigned char* lds, const int lda, const int ldb, const Sched& S, const Epi& E) {
;     ...
;     PG8_WAIT_V(0);
;     PG8_BAR;
; __global__ void __launch_bounds__(512, 2) mega_fwd(Params P) {
;     ...
;         PH(10) { PHASE_BEGIN
;           pg8::BranchOrder S{P5, WBR, LDP, 1024, MP / 256, 8, G, c, 16, 4}; pg8::EpiG2 E{GT, (u32x4*)(ws + WS_XH) + (size_t)c * 16 * 512, HB, PART2, 4};
;           pg8::gemm_phase(lds, LDP, 1024, S, E); }
;         GSYNC();
.LBB0_1297:
	s_waitcnt vmcnt(0)
	v_readlane_b32 s94, v254, 36
	v_readlane_b32 s96, v254, 38
	v_readlane_b32 s90, v254, 40
	v_readlane_b32 s88, v254, 42
	v_readlane_b32 s92, v254, 44
	v_readlane_b32 s74, v254, 46
	v_readlane_b32 s95, v254, 37
	v_readlane_b32 s97, v254, 39
	v_readlane_b32 s91, v254, 41
	v_readlane_b32 s89, v254, 43
	v_readlane_b32 s93, v254, 45
	v_readlane_b32 s75, v254, 47
	s_movk_i32 s71, 0x1ff
	s_barrier
	s_cmpk_lt_u32 s2, 0x60
	s_cbranch_scc1 .Lw_skip_g2
	v_writelane_b32 v255, s0, 8
	s_nop 1
	v_writelane_b32 v255, s1, 9
	s_nop 1
	v_writelane_b32 v255, s4, 10
	s_nop 1
	v_writelane_b32 v255, s5, 11
	s_nop 1
	v_writelane_b32 v255, s14, 12
	s_nop 1
	v_writelane_b32 v255, s15, 13
	s_nop 1
	v_writelane_b32 v255, s16, 14
	s_nop 1
	v_writelane_b32 v255, s17, 15
	s_nop 1
	v_writelane_b32 v255, s18, 16
	s_nop 1
	v_writelane_b32 v255, s19, 17
	s_nop 1
	v_writelane_b32 v255, s24, 18
	s_nop 1
	v_writelane_b32 v255, s25, 19
	s_nop 1
	v_writelane_b32 v255, s28, 20
	s_nop 1
	v_writelane_b32 v255, s29, 21
	s_nop 1
	v_writelane_b32 v255, s30, 22
	s_nop 1
	v_writelane_b32 v255, s31, 23
	s_nop 1
	v_writelane_b32 v255, s34, 24
	s_nop 1
	v_writelane_b32 v255, s35, 25
	s_nop 1
	v_writelane_b32 v255, s40, 26
	s_nop 1
	v_writelane_b32 v255, s41, 27
	s_nop 1
	v_writelane_b32 v255, s42, 28
	s_nop 1
	v_writelane_b32 v255, s43, 29
	s_nop 1
	v_writelane_b32 v255, s44, 30
	s_nop 1
	v_writelane_b32 v255, s45, 31
	s_nop 1
	v_writelane_b32 v255, s46, 32
	s_nop 1
	v_writelane_b32 v255, s47, 33
	s_nop 1
	v_writelane_b32 v255, s48, 34
	s_nop 1
	v_writelane_b32 v255, s49, 35
	s_nop 1
	v_writelane_b32 v255, s50, 36
	s_nop 1
	v_writelane_b32 v255, s53, 37
	s_nop 1
	v_writelane_b32 v255, s54, 38
	s_nop 1
	v_writelane_b32 v255, s55, 39
	s_nop 1
	v_writelane_b32 v255, s56, 40
	s_nop 1
	v_writelane_b32 v255, s57, 41
	s_nop 1
	v_writelane_b32 v255, s68, 42
	s_nop 1
	v_writelane_b32 v255, s73, 43
	s_nop 1
	s_movk_i32 s73, 0x2000
	s_movk_i32 s50, 0x6000
	s_mov_b32 s53, 0x8000
	s_mov_b32 s54, 0xa000
	s_mov_b32 s55, 0xc000
	s_mov_b32 s56, 0xe000
	s_mov_b32 s57, 0x16000
	s_movk_i32 s100, 0xa0
	s_sub_u32 s101, s2, 0x60
	s_lshl_b32 s101, s101, 3
	s_mov_b32 s4, 0x400
	v_writelane_b32 v255, s4, 50
	s_nop 1
	s_mov_b32 s4, 0x1e00
	v_writelane_b32 v255, s4, 51
	s_nop 1
	s_mov_b32 s4, 0x3
	v_writelane_b32 v255, s4, 54
	s_nop 1
	s_branch .Ltr_w1_entry
.Lw1_ret_g2:
	s_mov_b64 exec, -1
	s_waitcnt vmcnt(0) lgkmcnt(0)
	s_movk_i32 s73, 0x2000
	s_movk_i32 s100, 0xa0
	s_sub_u32 s101, s2, 0x60
	s_lshl_b32 s101, s101, 3
	s_mov_b32 s4, 0x300
	v_writelane_b32 v255, s4, 50
	s_nop 1
	s_mov_b32 s4, 0x3f0
	v_writelane_b32 v255, s4, 51
	s_nop 1
	s_mov_b32 s4, 0x3
	v_writelane_b32 v255, s4, 53
	s_nop 1
	s_branch .Lw2_entry
.Lw2_ret_g2:
	s_mov_b64 exec, -1
	s_waitcnt vmcnt(0) lgkmcnt(0)
	v_readlane_b32 s0, v255, 8
	v_readlane_b32 s1, v255, 9
	v_readlane_b32 s4, v255, 10
	v_readlane_b32 s5, v255, 11
	v_readlane_b32 s14, v255, 12
	v_readlane_b32 s15, v255, 13
	v_readlane_b32 s16, v255, 14
	v_readlane_b32 s17, v255, 15
	v_readlane_b32 s18, v255, 16
	v_readlane_b32 s19, v255, 17
	v_readlane_b32 s24, v255, 18
	v_readlane_b32 s25, v255, 19
	v_readlane_b32 s28, v255, 20
	v_readlane_b32 s29, v255, 21
	v_readlane_b32 s30, v255, 22
	v_readlane_b32 s31, v255, 23
	v_readlane_b32 s34, v255, 24
	v_readlane_b32 s35, v255, 25
	v_readlane_b32 s40, v255, 26
	v_readlane_b32 s41, v255, 27
	v_readlane_b32 s42, v255, 28
	v_readlane_b32 s43, v255, 29
	v_readlane_b32 s44, v255, 30
	v_readlane_b32 s45, v255, 31
	v_readlane_b32 s46, v255, 32
	v_readlane_b32 s47, v255, 33
	v_readlane_b32 s48, v255, 34
	v_readlane_b32 s49, v255, 35
	v_readlane_b32 s50, v255, 36
	v_readlane_b32 s53, v255, 37
	v_readlane_b32 s54, v255, 38
	v_readlane_b32 s55, v255, 39
	v_readlane_b32 s56, v255, 40
	v_readlane_b32 s57, v255, 41
	v_readlane_b32 s68, v255, 42
	v_readlane_b32 s73, v255, 43
	s_nop 4

; #define PG8_WAIT_V(n) asm volatile("s_waitcnt vmcnt(" #n ")" ::: "memory")
; #define PG8_BAR __builtin_amdgcn_s_barrier()
; #define PH(b) if ((PHM >> (b)) & 1)
; #define PHASE_BEGIN unsigned char* ws = opaque_ptr(P.ws); const int z = opaque_zero(); (void)ws; (void)z;
; template <class Epi, class Sched>
; __device__ __forceinline__ void gemm_phase(LAS unsigned char* lds, const int lda, const int ldb, const Sched& S, const Epi& E) {
;     ...
;     PG8_WAIT_V(0);
;     PG8_BAR;
; __global__ void __launch_bounds__(512, 2) mega_fwd(Params P) {
;     ...
;         PH(11) { PHASE_BEGIN
;           pg8::SplitOrder S{HB, WOUT, D, D, MP / 256, 8, G, c, D / 64, 4, 8}; pg8::EpiMix E{MIX, D, PART, 4};
;           pg8::gemm_phase(lds, D, D, S, E); }
.LBB0_1499:
	s_waitcnt vmcnt(0)
	v_readlane_b32 s90, v254, 40
	v_readlane_b32 s88, v254, 42
	v_readlane_b32 s74, v254, 46
	v_readlane_b32 s91, v254, 41
	v_readlane_b32 s89, v254, 43
	v_readlane_b32 s75, v254, 47
	s_movk_i32 s71, 0x1ff
	s_barrier
	s_cmpk_lt_u32 s2, 0x20
	s_cbranch_scc1 .Lw2_skip_g3
	v_writelane_b32 v255, s0, 8
	s_nop 1
	v_writelane_b32 v255, s1, 9
	s_nop 1
	v_writelane_b32 v255, s4, 10
	s_nop 1
	v_writelane_b32 v255, s5, 11
	s_nop 1
	v_writelane_b32 v255, s14, 12
	s_nop 1
	v_writelane_b32 v255, s15, 13
	s_nop 1
	v_writelane_b32 v255, s16, 14
	s_nop 1
	v_writelane_b32 v255, s17, 15
	s_nop 1
	v_writelane_b32 v255, s18, 16
	s_nop 1
	v_writelane_b32 v255, s19, 17
	s_nop 1
	v_writelane_b32 v255, s24, 18
	s_nop 1
	v_writelane_b32 v255, s25, 19
	s_nop 1
	v_writelane_b32 v255, s28, 20
	s_nop 1
	v_writelane_b32 v255, s29, 21
	s_nop 1
	v_writelane_b32 v255, s30, 22
	s_nop 1
	v_writelane_b32 v255, s31, 23
	s_nop 1
	v_writelane_b32 v255, s68, 24
	s_nop 1
	v_writelane_b32 v255, s73, 25
	s_nop 1
	s_movk_i32 s73, 0x2000
	s_movk_i32 s100, 0xe0
	s_sub_u32 s101, s2, 0x20
	s_lshl_b32 s101, s101, 3
	s_mov_b32 s4, 0xf10
	v_writelane_b32 v255, s4, 50
	s_nop 1
	s_mov_b32 s4, 0x6f0
	v_writelane_b32 v255, s4, 51
	s_nop 1
	s_mov_b32 s4, 0x4
	v_writelane_b32 v255, s4, 53
	s_nop 1
	s_branch .Lw2_entry
